# S1: short-conv pass: second item's tap weights fetched together with the first item's (duplicate loads) instead of a second round trip; bytes after it unchanged; on top of K1+R1
# speedup vs baseline: 1.0093x; 1.0093x over previous
; __device__ __forceinline__ void unpack8(const u32x4& w, float (&f)[8]) { f[0] = bf_lo(w.x); f[1] = bf_hi(w.x); f[2] = bf_lo(w.y); f[3] = bf_hi(w.y); f[4] = bf_lo(w.z); f[5] = bf_hi(w.z); f[6] = bf_lo(w.w); f[7] = bf_hi(w.w); }
; __device__ __forceinline__ void sconv_pass(const Args& a, int e, int nrows, int gt, int NT) {
;     const bf16_t* U = (const bf16_t*)(a.ws + WS_BIG); bf16_t* MIXo = (bf16_t*)(a.ws + WS_MIX); const float* cw = a.in[9] + (size_t)e * 3 * 512;
;     for (int idx0 = gt; idx0 < nrows * 64; idx0 += 2 * NT) {
;         u32x4 ld[2][7]; int rowi[2], chi[2]; float m0[2], m2[2]; bool ok[2];
; #pragma unroll
;         for (int u = 0; u < 2; ++u) {
;             const int idx = idx0 + u * NT; ok[u] = idx < nrows * 64; const int id = ok[u] ? idx : idx0;
;             const int row = id >> 6, ch = id & 63; rowi[u] = row; chi[u] = ch;
;             const int t = row < MX ? (row & (SEQ - 1)) : ((row - MX) & (CTXL - 1)), T = row < MX ? SEQ : CTXL;
;             m0[u] = t > 0 ? 1.f : 0.f; m2[u] = t < T - 1 ? 1.f : 0.f;
;             const bf16_t* up = U + (size_t)row * ATT_IN + 8 * ch; const ptrdiff_t dn = t > 0 ? -(ptrdiff_t)ATT_IN : 0, upo = t < T - 1 ? (ptrdiff_t)ATT_IN : 0;
;             ld[u][0] = ld16(up + 768);
;             ld[u][1] = ld16(up + dn + 1280); ld[u][2] = ld16(up + dn + 1792);
;             ld[u][3] = ld16(up + 1280); ld[u][4] = ld16(up + 1792);
;             ld[u][5] = ld16(up + upo + 1280); ld[u][6] = ld16(up + upo + 1792);
;         }
; #pragma unroll
;         for (int u = 0; u < 2; ++u) {
;             if (!ok[u]) continue;
;             const int ch = chi[u];
;             float bv[8], acc[8], cv[8], zv[8];
;             unpack8(ld[u][0], bv);
; #pragma unroll
;             for (int q = 0; q < 8; ++q) acc[q] = 0.f;
; #pragma unroll
;             for (int j = 0; j < 3; ++j) {
;                 unpack8(ld[u][1 + 2 * j], cv); unpack8(ld[u][2 + 2 * j], zv);
;                 const float mk = j == 0 ? m0[u] : (j == 2 ? m2[u] : 1.f);
;                 const f32x4 w0 = *(const f32x4*)(cw + j * 512 + 8 * ch) * mk, w1 = *(const f32x4*)(cw + j * 512 + 8 * ch + 4) * mk;
; #pragma unroll
;                 for (int q = 0; q < 4; ++q) { acc[q] += w0[q] * (cv[q] * zv[q]); acc[4 + q] += w1[q] * (cv[4 + q] * zv[4 + q]); }
.LBB0_246:
	v_ashrrev_i32_e32 v86, 6, v0
	s_movk_i32 s13, 0x4000
	v_cmp_gt_i32_e32 vcc, s13, v86
	v_readlane_b32 s16, v252, 21
	v_readlane_b32 s17, v252, 22
	v_cndmask_b32_e32 v1, v229, v230, vcc
	v_and_b32_e32 v2, v1, v86
	v_cmp_eq_u32_e32 vcc, 0, v2
	v_cmp_eq_u32_e64 s[34:35], v2, v1
	v_mov_b64_e32 v[2:3], s[16:17]
	v_and_b32_e32 v56, 0x1f8, v85
	v_mad_i64_i32 v[4:5], s[16:17], v86, s33, v[2:3]
	v_lshlrev_b32_e32 v90, 1, v56
	v_mov_b32_e32 v91, v81
	v_lshl_add_u64 v[44:45], v[4:5], 0, v[90:91]
	v_cndmask_b32_e64 v80, v233, 0, s[34:35]
	v_add_u32_e32 v89, s5, v0
	v_lshl_add_u64 v[4:5], v[44:45], 0, v[80:81]
	v_cmp_gt_i32_e64 s[36:37], s4, v89
	global_load_dwordx4 v[36:39], v[44:45], off offset:2560
	global_load_dwordx4 v[40:43], v[44:45], off offset:3584
	global_load_dwordx4 v[32:35], v[4:5], off offset:2560
	global_load_dwordx4 v[28:31], v[4:5], off offset:3584
	v_cndmask_b32_e64 v4, v0, v89, s[36:37]
	v_ashrrev_i32_e32 v82, 6, v4
	v_cndmask_b32_e64 v88, 1.0, 0, s[34:35]
	v_cmp_gt_i32_e64 s[34:35], s13, v82
	v_mov_b32_e32 v5, v81
	v_cndmask_b32_e64 v47, -1, 0, vcc
	v_cndmask_b32_e64 v0, v229, v230, s[34:35]
	v_and_b32_e32 v1, v0, v82
	v_cmp_eq_u32_e64 s[34:35], 0, v1
	v_cmp_eq_u32_e64 s[38:39], v1, v0
	v_mad_i64_i32 v[0:1], s[16:17], v82, s33, v[2:3]
	v_lshlrev_b32_e32 v2, 3, v4
	v_and_b32_e32 v93, 0x1f8, v2
	v_lshlrev_b32_e32 v80, 1, v93
	v_lshl_add_u64 v[0:1], v[0:1], 0, v[80:81]
	v_cndmask_b32_e64 v3, -1, 0, s[34:35]
	v_cndmask_b32_e64 v2, v238, 0, s[34:35]
	v_cndmask_b32_e64 v4, v233, 0, s[38:39]
	v_lshl_add_u64 v[2:3], v[0:1], 0, v[2:3]
	v_cndmask_b32_e64 v46, v238, 0, vcc
	global_load_dwordx4 v[24:27], v[0:1], off offset:1536
	global_load_dwordx4 v[20:23], v[2:3], off offset:2560
	global_load_dwordx4 v[16:19], v[2:3], off offset:3584
	s_waitcnt lgkmcnt(0)
	global_load_dwordx4 v[8:11], v[0:1], off offset:2560
	global_load_dwordx4 v[12:15], v[0:1], off offset:3584
	v_lshl_add_u64 v[0:1], v[0:1], 0, v[4:5]
	v_lshl_add_u64 v[46:47], v[44:45], 0, v[46:47]
	global_load_dwordx4 v[4:7], v[0:1], off offset:2560
	s_nop 0
	global_load_dwordx4 v[0:3], v[0:1], off offset:3584
	s_nop 0
	global_load_dwordx4 v[48:51], v[46:47], off offset:3584
	global_load_dwordx4 v[52:55], v[46:47], off offset:2560
	global_load_dwordx4 v[60:63], v[44:45], off offset:1536
	v_lshlrev_b32_e32 v64, 2, v56
	v_mov_b32_e32 v65, v81
	v_lshl_add_u64 v[72:73], s[8:9], 0, v[64:65]
	s_mov_b64 s[16:17], 0x1000
	v_cndmask_b32_e64 v92, 1.0, 0, vcc
	global_load_dwordx4 v[104:107], v64, s[8:9] offset:16
	global_load_dwordx4 v[44:47], v64, s[8:9] offset:16
	global_load_dwordx4 v[108:111], v64, s[8:9]
	global_load_dwordx4 v[68:71], v64, s[8:9]
	global_load_dwordx4 v[112:115], v64, s[8:9] offset:2064
	global_load_dwordx4 v[56:59], v64, s[8:9] offset:2064
	s_nop 0
	global_load_dwordx4 v[116:119], v64, s[8:9] offset:2048
	global_load_dwordx4 v[64:67], v64, s[8:9] offset:2048
	v_lshl_add_u64 v[76:77], v[72:73], 0, s[16:17]
	v_add_co_u32_e32 v72, vcc, s94, v72
	v_ashrrev_i32_e32 v87, 31, v86
	s_nop 0
	v_addc_co_u32_e32 v73, vcc, 0, v73, vcc
	global_load_dwordx4 v[120:123], v[72:73], off
	global_load_dwordx4 v[72:75], v[72:73], off
	s_nop 0
	global_load_dwordx4 v[124:127], v[76:77], off offset:16
	global_load_dwordx4 v[76:79], v[76:77], off offset:16
	s_waitcnt vmcnt(25)
	v_lshlrev_b32_e32 v102, 16, v36
	s_waitcnt vmcnt(24)
	v_lshlrev_b32_e32 v100, 16, v40
	v_and_b32_e32 v101, 0xffff0000, v40
	v_and_b32_e32 v103, 0xffff0000, v36
	v_lshlrev_b32_e32 v40, 16, v41
	v_and_b32_e32 v41, 0xffff0000, v41
	v_lshlrev_b32_e32 v36, 16, v37
	v_and_b32_e32 v37, 0xffff0000, v37
	v_pk_mul_f32 v[36:37], v[36:37], v[40:41]
	s_waitcnt vmcnt(22)
	v_lshlrev_b32_e32 v40, 16, v29
	v_and_b32_e32 v41, 0xffff0000, v29
	s_waitcnt vmcnt(14)
	v_lshlrev_b32_e32 v98, 16, v48
	s_waitcnt vmcnt(13)
	v_lshlrev_b32_e32 v96, 16, v52
	v_and_b32_e32 v97, 0xffff0000, v52
	v_and_b32_e32 v99, 0xffff0000, v48
	v_pk_mul_f32 v[96:97], v[98:99], v[96:97]
	s_waitcnt vmcnt(12)
	v_lshlrev_b32_e32 v94, 16, v60
	s_waitcnt vmcnt(8)
	v_pk_mul_f32 v[68:69], v[92:93], v[68:69] op_sel_hi:[0,1]
	v_pk_fma_f32 v[68:69], v[96:97], v[68:69], 0 op_sel_hi:[1,1,0]
	v_pk_mul_f32 v[96:97], v[102:103], v[100:101]
	v_and_b32_e32 v95, 0xffff0000, v60
	s_waitcnt vmcnt(4)
	v_pk_fma_f32 v[64:65], v[96:97], v[64:65], v[68:69]
	v_lshlrev_b32_e32 v68, 16, v32
	v_and_b32_e32 v69, 0xffff0000, v32
	v_lshlrev_b32_e32 v96, 16, v28
	v_and_b32_e32 v97, 0xffff0000, v28
	s_waitcnt vmcnt(2)
	v_pk_mul_f32 v[72:73], v[88:89], v[72:73] op_sel_hi:[0,1]
	v_pk_mul_f32 v[68:69], v[68:69], v[96:97]
	v_lshlrev_b32_e32 v52, 16, v53
	v_pk_fma_f32 v[64:65], v[68:69], v[72:73], v[64:65]
	v_and_b32_e32 v53, 0xffff0000, v53
	v_pk_mul_f32 v[64:65], v[64:65], v[94:95]
	v_lshlrev_b32_e32 v48, 16, v49
	v_and_b32_e32 v49, 0xffff0000, v49
	v_cvt_pk_bf16_f32 v28, v64, v65
	v_pk_mul_f32 v[64:65], v[92:93], v[70:71] op_sel_hi:[0,1]
	v_pk_mul_f32 v[48:49], v[48:49], v[52:53]
	v_lshlrev_b32_e32 v32, 16, v33
	v_pk_fma_f32 v[48:49], v[48:49], v[64:65], 0 op_sel_hi:[1,1,0]
	v_and_b32_e32 v33, 0xffff0000, v33
	v_pk_fma_f32 v[36:37], v[36:37], v[66:67], v[48:49]
	v_pk_mul_f32 v[48:49], v[88:89], v[74:75] op_sel_hi:[0,1]
	v_pk_mul_f32 v[32:33], v[32:33], v[40:41]
	v_lshlrev_b32_e32 v40, 16, v50
	v_pk_fma_f32 v[32:33], v[32:33], v[48:49], v[36:37]
	v_lshlrev_b32_e32 v36, 16, v54
	v_and_b32_e32 v37, 0xffff0000, v54
	v_and_b32_e32 v41, 0xffff0000, v50
	v_lshlrev_b32_e32 v48, 16, v42
	v_and_b32_e32 v49, 0xffff0000, v42
	v_lshlrev_b32_e32 v52, 16, v38
	v_and_b32_e32 v53, 0xffff0000, v38
	v_pk_mul_f32 v[44:45], v[92:93], v[44:45] op_sel_hi:[0,1]
	v_pk_mul_f32 v[36:37], v[40:41], v[36:37]
	v_pk_mul_f32 v[40:41], v[52:53], v[48:49]
	v_pk_fma_f32 v[36:37], v[44:45], v[36:37], 0 op_sel_hi:[1,1,0]
	v_lshlrev_b32_e32 v60, 16, v61
	v_and_b32_e32 v61, 0xffff0000, v61
	v_pk_fma_f32 v[36:37], v[40:41], v[56:57], v[36:37]
	v_lshlrev_b32_e32 v40, 16, v34
	v_and_b32_e32 v41, 0xffff0000, v34
	v_lshlrev_b32_e32 v44, 16, v30
	v_and_b32_e32 v45, 0xffff0000, v30
	v_pk_mul_f32 v[32:33], v[32:33], v[60:61]
	s_waitcnt vmcnt(0)
; __device__ __forceinline__ unsigned cvt_pk_bf16(float lo, float hi) { f32x2_t v = {lo, hi}; bf16x2_t b = __builtin_convertvector(v, bf16x2_t); return __builtin_bit_cast(unsigned, b); }
; __device__ __forceinline__ void unpack8(const u32x4& w, float (&f)[8]) { f[0] = bf_lo(w.x); f[1] = bf_hi(w.x); f[2] = bf_lo(w.y); f[3] = bf_hi(w.y); f[4] = bf_lo(w.z); f[5] = bf_hi(w.z); f[6] = bf_lo(w.w); f[7] = bf_hi(w.w); }
; __device__ __forceinline__ void sconv_pass(const Args& a, int e, int nrows, int gt, int NT) {
;     ...
; #pragma unroll
;         for (int u = 0; u < 2; ++u) {
;             if (!ok[u]) continue;
;             const int ch = chi[u];
;             float bv[8], acc[8], cv[8], zv[8];
;             unpack8(ld[u][0], bv);
; #pragma unroll
;             for (int q = 0; q < 8; ++q) acc[q] = 0.f;
; #pragma unroll
;             for (int j = 0; j < 3; ++j) {
;                 unpack8(ld[u][1 + 2 * j], cv); unpack8(ld[u][2 + 2 * j], zv);
;                 const float mk = j == 0 ? m0[u] : (j == 2 ? m2[u] : 1.f);
;                 const f32x4 w0 = *(const f32x4*)(cw + j * 512 + 8 * ch) * mk, w1 = *(const f32x4*)(cw + j * 512 + 8 * ch + 4) * mk;
; #pragma unroll
;                 for (int q = 0; q < 4; ++q) { acc[q] += w0[q] * (cv[q] * zv[q]); acc[4 + q] += w1[q] * (cv[4 + q] * zv[4 + q]); }
;             }
;             u32x4 w; w.x = cvt_pk_bf16(bv[0] * acc[0], bv[1] * acc[1]); w.y = cvt_pk_bf16(bv[2] * acc[2], bv[3] * acc[3]); w.z = cvt_pk_bf16(bv[4] * acc[4], bv[5] * acc[5]); w.w = cvt_pk_bf16(bv[6] * acc[6], bv[7] * acc[7]);
;             *(u32x4*)(MIXo + (size_t)rowi[u] * KMO + 512 + 8 * ch) = w;
;         }
	v_pk_mul_f32 v[48:49], v[88:89], v[76:77] op_sel_hi:[0,1]
	v_pk_mul_f32 v[40:41], v[40:41], v[44:45]
	v_cvt_pk_bf16_f32 v29, v32, v33
	v_lshlrev_b32_e32 v32, 16, v62
	v_and_b32_e32 v33, 0xffff0000, v62
	v_pk_fma_f32 v[36:37], v[40:41], v[48:49], v[36:37]
	v_lshlrev_b32_e32 v40, 16, v51
	v_pk_mul_f32 v[32:33], v[36:37], v[32:33]
	v_lshlrev_b32_e32 v36, 16, v55
	v_and_b32_e32 v37, 0xffff0000, v55
	v_and_b32_e32 v41, 0xffff0000, v51
	v_lshlrev_b32_e32 v42, 16, v43
	v_and_b32_e32 v43, 0xffff0000, v43
	v_lshlrev_b32_e32 v38, 16, v39
	v_and_b32_e32 v39, 0xffff0000, v39
	v_pk_mul_f32 v[44:45], v[92:93], v[46:47] op_sel_hi:[0,1]
	v_pk_mul_f32 v[36:37], v[40:41], v[36:37]
	v_pk_mul_f32 v[38:39], v[38:39], v[42:43]
	v_pk_fma_f32 v[36:37], v[44:45], v[36:37], 0 op_sel_hi:[1,1,0]
	v_lshlrev_b32_e32 v34, 16, v35
	v_pk_fma_f32 v[36:37], v[38:39], v[58:59], v[36:37]
	v_and_b32_e32 v35, 0xffff0000, v35
	v_lshlrev_b32_e32 v38, 16, v31
	v_and_b32_e32 v39, 0xffff0000, v31
	v_pk_mul_f32 v[40:41], v[88:89], v[78:79] op_sel_hi:[0,1]
	v_pk_mul_f32 v[34:35], v[34:35], v[38:39]
	v_cvt_pk_bf16_f32 v30, v32, v33
	v_lshlrev_b32_e32 v32, 16, v63
	v_and_b32_e32 v33, 0xffff0000, v63
	v_pk_fma_f32 v[34:35], v[34:35], v[40:41], v[36:37]
	s_nop 0
	v_pk_mul_f32 v[32:33], v[34:35], v[32:33]
	s_nop 0
	v_cvt_pk_bf16_f32 v31, v32, v33
	v_lshlrev_b64 v[32:33], 11, v[86:87]
	v_lshl_add_u64 v[32:33], s[86:87], 0, v[32:33]
	v_lshl_add_u64 v[32:33], v[32:33], 0, v[90:91]
	v_add_co_u32_e32 v32, vcc, 0x12500000, v32
	s_nop 1
	v_addc_co_u32_e32 v33, vcc, 0, v33, vcc
	global_store_dwordx4 v[32:33], v[28:31], off offset:1024 sc1
	s_and_saveexec_b64 s[42:43], s[36:37]
	s_cbranch_execz .LBB0_245
	v_cndmask_b32_e64 v42, 1.0, 0, s[34:35]
	s_nop 0
	s_nop 0
	v_lshlrev_b32_e32 v58, 16, v20
	v_and_b32_e32 v59, 0xffff0000, v20
	v_lshlrev_b32_e32 v60, 16, v16
	v_and_b32_e32 v61, 0xffff0000, v16
	v_lshlrev_b32_e32 v62, 16, v12
	v_and_b32_e32 v63, 0xffff0000, v12
	v_lshlrev_b32_e32 v64, 16, v8
	v_and_b32_e32 v65, 0xffff0000, v8
	v_pk_mul_f32 v[58:59], v[58:59], v[60:61]
	v_cndmask_b32_e64 v40, 1.0, 0, s[38:39]
	v_lshlrev_b32_e32 v56, 16, v24
	v_and_b32_e32 v57, 0xffff0000, v24
	v_lshlrev_b32_e32 v20, 16, v21
	v_and_b32_e32 v21, 0xffff0000, v21
	v_lshlrev_b32_e32 v16, 16, v17
	v_and_b32_e32 v17, 0xffff0000, v17
	v_lshlrev_b32_e32 v12, 16, v13
	v_and_b32_e32 v13, 0xffff0000, v13
	v_lshlrev_b32_e32 v8, 16, v9
	v_and_b32_e32 v9, 0xffff0000, v9
	v_pk_mul_f32 v[16:17], v[20:21], v[16:17]
	v_pk_mul_f32 v[8:9], v[8:9], v[12:13]
	v_lshlrev_b32_e32 v12, 16, v1
	v_and_b32_e32 v13, 0xffff0000, v1
	v_lshlrev_b32_e32 v24, 16, v25
	v_and_b32_e32 v25, 0xffff0000, v25
	v_lshlrev_b32_e32 v20, 16, v10
	v_and_b32_e32 v21, 0xffff0000, v10
	v_lshlrev_b32_e32 v10, 16, v11
	v_and_b32_e32 v11, 0xffff0000, v11
	v_ashrrev_i32_e32 v83, 31, v82
	v_pk_mul_f32 v[44:45], v[42:43], v[108:109] op_sel_hi:[0,1]
	v_pk_fma_f32 v[44:45], v[58:59], v[44:45], 0 op_sel_hi:[1,1,0]
	v_pk_mul_f32 v[58:59], v[64:65], v[62:63]
	v_pk_mul_f32 v[52:53], v[40:41], v[120:121] op_sel_hi:[0,1]
	v_pk_fma_f32 v[44:45], v[58:59], v[116:117], v[44:45]
	v_lshlrev_b32_e32 v48, 16, v4
	v_and_b32_e32 v49, 0xffff0000, v4
	v_lshlrev_b32_e32 v58, 16, v0
	v_and_b32_e32 v59, 0xffff0000, v0
	v_pk_mul_f32 v[48:49], v[48:49], v[58:59]
	v_lshlrev_b32_e32 v4, 16, v5
	v_pk_fma_f32 v[44:45], v[48:49], v[52:53], v[44:45]
	v_and_b32_e32 v5, 0xffff0000, v5
	v_pk_mul_f32 v[44:45], v[44:45], v[56:57]
	v_pk_mul_f32 v[4:5], v[4:5], v[12:13]
	v_cvt_pk_bf16_f32 v0, v44, v45
	v_pk_mul_f32 v[44:45], v[42:43], v[110:111] op_sel_hi:[0,1]
	v_pk_fma_f32 v[16:17], v[16:17], v[44:45], 0 op_sel_hi:[1,1,0]
	v_lshlrev_b32_e32 v12, 16, v18
	v_pk_fma_f32 v[8:9], v[8:9], v[118:119], v[16:17]
	v_pk_mul_f32 v[16:17], v[40:41], v[122:123] op_sel_hi:[0,1]
	v_pk_fma_f32 v[4:5], v[4:5], v[16:17], v[8:9]
	v_lshlrev_b32_e32 v8, 16, v22
	v_and_b32_e32 v9, 0xffff0000, v22
	v_and_b32_e32 v13, 0xffff0000, v18
	v_pk_mul_f32 v[4:5], v[4:5], v[24:25]
	v_lshlrev_b32_e32 v16, 16, v14
	v_and_b32_e32 v17, 0xffff0000, v14
	v_pk_mul_f32 v[24:25], v[42:43], v[104:105] op_sel_hi:[0,1]
	v_pk_mul_f32 v[8:9], v[8:9], v[12:13]
	v_pk_mul_f32 v[12:13], v[20:21], v[16:17]
	v_pk_fma_f32 v[8:9], v[8:9], v[24:25], 0 op_sel_hi:[1,1,0]
	v_lshlrev_b32_e32 v16, 16, v2
	v_pk_fma_f32 v[8:9], v[12:13], v[112:113], v[8:9]
	v_lshlrev_b32_e32 v12, 16, v6
	v_and_b32_e32 v13, 0xffff0000, v6
	v_and_b32_e32 v17, 0xffff0000, v2
	v_pk_mul_f32 v[20:21], v[40:41], v[124:125] op_sel_hi:[0,1]
	v_pk_mul_f32 v[12:13], v[12:13], v[16:17]
	v_cvt_pk_bf16_f32 v1, v4, v5
	v_lshlrev_b32_e32 v4, 16, v26
	v_and_b32_e32 v5, 0xffff0000, v26
	v_pk_fma_f32 v[8:9], v[12:13], v[20:21], v[8:9]
	v_lshlrev_b32_e32 v12, 16, v19
	v_pk_mul_f32 v[4:5], v[8:9], v[4:5]
	v_lshlrev_b32_e32 v8, 16, v23
	v_and_b32_e32 v9, 0xffff0000, v23
	v_and_b32_e32 v13, 0xffff0000, v19
	v_lshlrev_b32_e32 v14, 16, v15
	v_and_b32_e32 v15, 0xffff0000, v15
	v_pk_mul_f32 v[16:17], v[42:43], v[106:107] op_sel_hi:[0,1]
	v_pk_mul_f32 v[8:9], v[8:9], v[12:13]
	v_pk_mul_f32 v[10:11], v[10:11], v[14:15]
	v_pk_fma_f32 v[8:9], v[8:9], v[16:17], 0 op_sel_hi:[1,1,0]
	v_lshlrev_b32_e32 v6, 16, v7
	v_pk_fma_f32 v[8:9], v[10:11], v[114:115], v[8:9]
	v_and_b32_e32 v7, 0xffff0000, v7
	v_lshlrev_b32_e32 v10, 16, v3
	v_and_b32_e32 v11, 0xffff0000, v3
	v_pk_mul_f32 v[12:13], v[40:41], v[126:127] op_sel_hi:[0,1]
	v_pk_mul_f32 v[6:7], v[6:7], v[10:11]
	v_cvt_pk_bf16_f32 v2, v4, v5
	v_lshlrev_b32_e32 v4, 16, v27
	v_and_b32_e32 v5, 0xffff0000, v27
	v_pk_fma_f32 v[6:7], v[6:7], v[12:13], v[8:9]
	s_nop 0
	v_pk_mul_f32 v[4:5], v[6:7], v[4:5]
	s_nop 0
	v_cvt_pk_bf16_f32 v3, v4, v5
	v_lshlrev_b64 v[4:5], 11, v[82:83]
	v_lshl_add_u64 v[4:5], s[86:87], 0, v[4:5]
	v_lshl_add_u64 v[4:5], v[4:5], 0, v[80:81]
	v_add_co_u32_e32 v4, vcc, 0x12500000, v4
	s_nop 1
	v_addc_co_u32_e32 v5, vcc, 0, v5, vcc
	global_store_dwordx4 v[4:5], v[0:3], off offset:1024 sc1
	s_branch .LBB0_245
	s_nop 0
	s_nop 0
	s_nop 0
	s_nop 0
	s_nop 0
	s_nop 0
	s_nop 0
	s_nop 0
	s_nop 0
	s_nop 0
	s_nop 0
